# stack13: + P10 merge LDS reads pipelined
# speedup vs baseline: 1.0015x; 1.0015x over previous
; __device__ __forceinline__ unsigned pk2(float lo, float hi) { return pg8::cvt_pk_bf16(lo, hi); }
;     ...
;     if (kh == 0) {
; #pragma unroll
;         for (int rb = 0; rb < 2; ++rb) {
;             float l = lrun[rb] + X[(rp * 68 + 66 + rb) * 64 + lane]; l += __shfl_xor(l, 16); l += __shfl_xor(l, 32);
;             const float inv = 1.0f / l;
;             bf16* orow = Op + (size_t)(32 * rp + 16 * rb + fr) * ldo + 4 * fq;
; #pragma unroll
;             for (int db = 0; db < 8; ++db) { float v[4];
; #pragma unroll
;                 for (int i = 0; i < 4; ++i) v[i] = (o[rb][db][i] + X[(rp * 68 + rb * 32 + db * 4 + i) * 64 + lane]) * inv;
;                 u32x2 ov; ov.x = pk2(v[0], v[1]); ov.y = pk2(v[2], v[3]); *(u32x2*)(orow + 16 * db) = ov; }
.LBB0_65:
	s_or_b64 exec, exec, s[36:37]
	s_waitcnt lgkmcnt(0)
	s_barrier
	s_and_saveexec_b64 s[36:37], vcc
	s_cbranch_execz .LBB0_44
	v_add3_u32 v10, 0, v5, v8
	ds_read_b32 v5, v10 offset:53760
	s_lshl_b64 s[14:15], s[74:75], 10
	s_add_u32 s0, s81, s14
	s_addc_u32 s15, s82, s15
	s_lshl_b32 s14, s85, 1
	s_waitcnt lgkmcnt(0)
	v_add_f32_e32 v5, v169, v5
	ds_bpermute_b32 v8, v193, v5
	s_add_u32 s14, s0, s14
	s_addc_u32 s15, s15, 0
	v_lshlrev_b32_e32 v152, 1, v156
	v_lshl_add_u64 v[6:7], s[14:15], 0, v[152:153]
	s_waitcnt lgkmcnt(0)
	v_add_f32_e32 v5, v5, v8
	ds_bpermute_b32 v8, v194, v5
	v_ashrrev_i32_e32 v161, 31, v160
	v_or_b32_e32 v4, 16, v160
	s_waitcnt lgkmcnt(0)
	v_add_f32_e32 v5, v5, v8
	v_div_scale_f32 v8, s[14:15], v5, v5, 1.0
	v_rcp_f32_e32 v9, v8
	s_nop 0
	v_fma_f32 v11, -v8, v9, 1.0
	v_fmac_f32_e32 v9, v11, v9
	v_div_scale_f32 v11, vcc, 1.0, v5, 1.0
	v_mul_f32_e32 v12, v11, v9
	v_fma_f32 v13, -v8, v12, v11
	v_fmac_f32_e32 v12, v13, v9
	v_fma_f32 v8, -v8, v12, v11
	v_div_fmas_f32 v8, v8, v9, v12
	ds_read2st64_b32 v[24:25], v10 offset0:144 offset1:145
	ds_read2st64_b32 v[28:29], v10 offset0:146 offset1:147
	ds_read2st64_b32 v[32:33], v10 offset0:148 offset1:149
	ds_read2st64_b32 v[36:37], v10 offset0:150 offset1:151
	ds_read2st64_b32 v[40:41], v10 offset0:152 offset1:153
	ds_read2st64_b32 v[44:45], v10 offset0:154 offset1:155
	ds_read2st64_b32 v[48:49], v10 offset0:156 offset1:157
	ds_read2st64_b32 v[52:53], v10 offset0:158 offset1:159
	v_div_fixup_f32 v5, v8, v5, 1.0
	v_lshlrev_b64 v[8:9], 10, v[160:161]
	v_lshl_add_u64 v[8:9], v[6:7], 0, v[8:9]
	s_waitcnt lgkmcnt(7)
	v_add_f32_e32 v11, v128, v24
	v_add_f32_e32 v12, v129, v25
	ds_read2st64_b32 v[56:57], v10 offset0:160 offset1:161
	v_mul_f32_e32 v14, v5, v12
	v_mul_f32_e32 v11, v11, v5
	s_waitcnt lgkmcnt(7)
	v_add_f32_e32 v12, v130, v28
	v_mul_f32_e32 v15, v5, v12
	v_add_f32_e32 v12, v131, v29
	ds_read2st64_b32 v[60:61], v10 offset0:162 offset1:163
	v_mul_f32_e32 v13, v5, v12
	v_cvt_pk_bf16_f32 v12, v11, v14
	v_cvt_pk_bf16_f32 v13, v15, v13
	global_store_dwordx2 v[8:9], v[12:13], off
	s_waitcnt lgkmcnt(7)
	v_add_f32_e32 v11, v124, v32
	v_add_f32_e32 v12, v125, v33
	ds_read2st64_b32 v[24:25], v10 offset0:164 offset1:165
	v_mul_f32_e32 v14, v5, v12
	v_mul_f32_e32 v11, v5, v11
	s_waitcnt lgkmcnt(7)
	v_add_f32_e32 v12, v126, v36
	v_mul_f32_e32 v15, v5, v12
	v_add_f32_e32 v12, v127, v37
	ds_read2st64_b32 v[28:29], v10 offset0:166 offset1:167
	v_mul_f32_e32 v13, v5, v12
	v_cvt_pk_bf16_f32 v12, v11, v14
	v_cvt_pk_bf16_f32 v13, v15, v13
	global_store_dwordx2 v[8:9], v[12:13], off offset:32
	s_waitcnt lgkmcnt(7)
	v_add_f32_e32 v11, v120, v40
	v_add_f32_e32 v12, v121, v41
	ds_read2st64_b32 v[32:33], v10 offset0:168 offset1:169
	v_mul_f32_e32 v14, v5, v12
	v_mul_f32_e32 v11, v5, v11
	s_waitcnt lgkmcnt(7)
	v_add_f32_e32 v12, v122, v44
	v_mul_f32_e32 v15, v5, v12
	v_add_f32_e32 v12, v123, v45
	ds_read2st64_b32 v[36:37], v10 offset0:170 offset1:171
	v_mul_f32_e32 v13, v5, v12
	v_cvt_pk_bf16_f32 v12, v11, v14
	v_cvt_pk_bf16_f32 v13, v15, v13
	global_store_dwordx2 v[8:9], v[12:13], off offset:64
	s_waitcnt lgkmcnt(7)
	v_add_f32_e32 v11, v116, v48
	v_add_f32_e32 v12, v117, v49
	ds_read2st64_b32 v[40:41], v10 offset0:172 offset1:173
	v_mul_f32_e32 v14, v5, v12
	v_mul_f32_e32 v11, v5, v11
	s_waitcnt lgkmcnt(7)
	v_add_f32_e32 v12, v118, v52
	v_mul_f32_e32 v15, v5, v12
	v_add_f32_e32 v12, v119, v53
	ds_read2st64_b32 v[44:45], v10 offset0:174 offset1:175
	v_mul_f32_e32 v13, v5, v12
	v_cvt_pk_bf16_f32 v12, v11, v14
	v_cvt_pk_bf16_f32 v13, v15, v13
	global_store_dwordx2 v[8:9], v[12:13], off offset:96
	s_waitcnt lgkmcnt(7)
	v_add_f32_e32 v11, v112, v56
	v_add_f32_e32 v12, v113, v57
	v_mul_f32_e32 v14, v5, v12
	v_mul_f32_e32 v11, v5, v11
	s_waitcnt lgkmcnt(6)
	v_add_f32_e32 v12, v114, v60
	v_mul_f32_e32 v15, v5, v12
	v_add_f32_e32 v12, v115, v61
	v_mul_f32_e32 v13, v5, v12
	v_cvt_pk_bf16_f32 v12, v11, v14
	v_cvt_pk_bf16_f32 v13, v15, v13
	global_store_dwordx2 v[8:9], v[12:13], off offset:128
	s_waitcnt lgkmcnt(5)
	v_add_f32_e32 v11, v108, v24
	v_add_f32_e32 v12, v109, v25
	v_mul_f32_e32 v14, v5, v12
	v_mul_f32_e32 v11, v5, v11
	s_waitcnt lgkmcnt(4)
	v_add_f32_e32 v12, v110, v28
	v_mul_f32_e32 v15, v5, v12
	v_add_f32_e32 v12, v111, v29
	v_mul_f32_e32 v13, v5, v12
	v_cvt_pk_bf16_f32 v12, v11, v14
	v_cvt_pk_bf16_f32 v13, v15, v13
	global_store_dwordx2 v[8:9], v[12:13], off offset:160
	s_waitcnt lgkmcnt(3)
	v_add_f32_e32 v11, v104, v32
	v_add_f32_e32 v12, v105, v33
	v_mul_f32_e32 v14, v5, v12
	v_mul_f32_e32 v11, v5, v11
	s_waitcnt lgkmcnt(2)
	v_add_f32_e32 v12, v106, v36
	v_mul_f32_e32 v15, v5, v12
	v_add_f32_e32 v12, v107, v37
	v_mul_f32_e32 v13, v5, v12
	v_cvt_pk_bf16_f32 v12, v11, v14
	v_cvt_pk_bf16_f32 v13, v15, v13
	global_store_dwordx2 v[8:9], v[12:13], off offset:192
	s_waitcnt lgkmcnt(1)
	v_add_f32_e32 v11, v100, v40
	v_add_f32_e32 v12, v101, v41
	v_mul_f32_e32 v14, v5, v12
	v_mul_f32_e32 v11, v5, v11
	s_waitcnt lgkmcnt(0)
; __device__ __forceinline__ unsigned pk2(float lo, float hi) { return pg8::cvt_pk_bf16(lo, hi); }
;     ...
;         for (int rb = 0; rb < 2; ++rb) {
;             float l = lrun[rb] + X[(rp * 68 + 66 + rb) * 64 + lane]; l += __shfl_xor(l, 16); l += __shfl_xor(l, 32);
;             const float inv = 1.0f / l;
;             bf16* orow = Op + (size_t)(32 * rp + 16 * rb + fr) * ldo + 4 * fq;
; #pragma unroll
;             for (int db = 0; db < 8; ++db) { float v[4];
; #pragma unroll
;                 for (int i = 0; i < 4; ++i) v[i] = (o[rb][db][i] + X[(rp * 68 + rb * 32 + db * 4 + i) * 64 + lane]) * inv;
;                 u32x2 ov; ov.x = pk2(v[0], v[1]); ov.y = pk2(v[2], v[3]); *(u32x2*)(orow + 16 * db) = ov; }
	v_add_f32_e32 v12, v102, v44
	v_mul_f32_e32 v15, v5, v12
	v_add_f32_e32 v12, v103, v45
	v_mul_f32_e32 v5, v5, v12
	v_cvt_pk_bf16_f32 v12, v11, v14
	v_cvt_pk_bf16_f32 v13, v15, v5
	ds_read_b32 v5, v10 offset:54016
	global_store_dwordx2 v[8:9], v[12:13], off offset:224
	s_waitcnt lgkmcnt(0)
	v_add_f32_e32 v5, v168, v5
	ds_bpermute_b32 v8, v193, v5
	s_waitcnt lgkmcnt(0)
	v_add_f32_e32 v5, v5, v8
	ds_bpermute_b32 v8, v194, v5
	s_waitcnt lgkmcnt(0)
	v_add_f32_e32 v5, v5, v8
	v_div_scale_f32 v8, s[14:15], v5, v5, 1.0
	v_rcp_f32_e32 v9, v8
	s_nop 0
	v_fma_f32 v11, -v8, v9, 1.0
	v_fmac_f32_e32 v9, v11, v9
	v_div_scale_f32 v11, vcc, 1.0, v5, 1.0
	v_mul_f32_e32 v12, v11, v9
	v_fma_f32 v13, -v8, v12, v11
	v_fmac_f32_e32 v12, v13, v9
	v_fma_f32 v8, -v8, v12, v11
	v_div_fmas_f32 v8, v8, v9, v12
	v_div_fixup_f32 v8, v8, v5, 1.0
	v_ashrrev_i32_e32 v5, 31, v4
	v_lshlrev_b64 v[4:5], 10, v[4:5]
	v_lshl_add_u64 v[4:5], v[6:7], 0, v[4:5]
	ds_read2st64_b32 v[24:25], v10 offset0:176 offset1:177
	ds_read2st64_b32 v[28:29], v10 offset0:178 offset1:179
	ds_read2st64_b32 v[32:33], v10 offset0:180 offset1:181
	ds_read2st64_b32 v[36:37], v10 offset0:182 offset1:183
	ds_read2st64_b32 v[40:41], v10 offset0:184 offset1:185
	ds_read2st64_b32 v[44:45], v10 offset0:186 offset1:187
	ds_read2st64_b32 v[48:49], v10 offset0:188 offset1:189
	ds_read2st64_b32 v[52:53], v10 offset0:190 offset1:191
	s_waitcnt lgkmcnt(7)
	v_add_f32_e32 v6, v96, v24
	v_mul_f32_e32 v9, v6, v8
	v_add_f32_e32 v6, v97, v25
	ds_read2st64_b32 v[56:57], v10 offset0:192 offset1:193
	v_mul_f32_e32 v11, v8, v6
	s_waitcnt lgkmcnt(7)
	v_add_f32_e32 v6, v98, v28
	v_mul_f32_e32 v12, v8, v6
	v_add_f32_e32 v6, v99, v29
	ds_read2st64_b32 v[60:61], v10 offset0:194 offset1:195
	v_mul_f32_e32 v7, v8, v6
	v_cvt_pk_bf16_f32 v6, v9, v11
	v_cvt_pk_bf16_f32 v7, v12, v7
	global_store_dwordx2 v[4:5], v[6:7], off
	s_waitcnt lgkmcnt(7)
	v_add_f32_e32 v6, v92, v32
	v_mul_f32_e32 v9, v8, v6
	v_add_f32_e32 v6, v93, v33
	ds_read2st64_b32 v[24:25], v10 offset0:196 offset1:197
	v_mul_f32_e32 v11, v8, v6
	s_waitcnt lgkmcnt(7)
	v_add_f32_e32 v6, v94, v36
	v_mul_f32_e32 v12, v8, v6
	v_add_f32_e32 v6, v95, v37
	ds_read2st64_b32 v[28:29], v10 offset0:198 offset1:199
	v_mul_f32_e32 v7, v8, v6
	v_cvt_pk_bf16_f32 v6, v9, v11
	v_cvt_pk_bf16_f32 v7, v12, v7
	global_store_dwordx2 v[4:5], v[6:7], off offset:32
	s_waitcnt lgkmcnt(7)
	v_add_f32_e32 v6, v84, v40
	v_mul_f32_e32 v9, v8, v6
	v_add_f32_e32 v6, v85, v41
	ds_read2st64_b32 v[32:33], v10 offset0:200 offset1:201
	v_mul_f32_e32 v11, v8, v6
	s_waitcnt lgkmcnt(7)
	v_add_f32_e32 v6, v86, v44
	v_mul_f32_e32 v12, v8, v6
	v_add_f32_e32 v6, v87, v45
	ds_read2st64_b32 v[36:37], v10 offset0:202 offset1:203
	v_mul_f32_e32 v7, v8, v6
	v_cvt_pk_bf16_f32 v6, v9, v11
	v_cvt_pk_bf16_f32 v7, v12, v7
	global_store_dwordx2 v[4:5], v[6:7], off offset:64
	s_waitcnt lgkmcnt(7)
	v_add_f32_e32 v6, v76, v48
	v_mul_f32_e32 v9, v8, v6
	v_add_f32_e32 v6, v77, v49
	ds_read2st64_b32 v[40:41], v10 offset0:204 offset1:205
	v_mul_f32_e32 v11, v8, v6
	s_waitcnt lgkmcnt(7)
	v_add_f32_e32 v6, v78, v52
	v_mul_f32_e32 v12, v8, v6
	v_add_f32_e32 v6, v79, v53
	ds_read2st64_b32 v[44:45], v10 offset0:206 offset1:207
	v_mul_f32_e32 v7, v8, v6
	v_cvt_pk_bf16_f32 v6, v9, v11
	v_cvt_pk_bf16_f32 v7, v12, v7
	global_store_dwordx2 v[4:5], v[6:7], off offset:96
	s_waitcnt lgkmcnt(7)
	v_add_f32_e32 v6, v72, v56
	v_mul_f32_e32 v9, v8, v6
	v_add_f32_e32 v6, v73, v57
	v_mul_f32_e32 v11, v8, v6
	s_waitcnt lgkmcnt(6)
	v_add_f32_e32 v6, v74, v60
	v_mul_f32_e32 v12, v8, v6
	v_add_f32_e32 v6, v75, v61
	v_mul_f32_e32 v7, v8, v6
	v_cvt_pk_bf16_f32 v6, v9, v11
	v_cvt_pk_bf16_f32 v7, v12, v7
	global_store_dwordx2 v[4:5], v[6:7], off offset:128
	s_waitcnt lgkmcnt(5)
	v_add_f32_e32 v6, v68, v24
	v_mul_f32_e32 v9, v8, v6
	v_add_f32_e32 v6, v69, v25
	v_mul_f32_e32 v11, v8, v6
	s_waitcnt lgkmcnt(4)
	v_add_f32_e32 v6, v70, v28
	v_mul_f32_e32 v12, v8, v6
	v_add_f32_e32 v6, v71, v29
	v_mul_f32_e32 v7, v8, v6
	v_cvt_pk_bf16_f32 v6, v9, v11
	v_cvt_pk_bf16_f32 v7, v12, v7
	global_store_dwordx2 v[4:5], v[6:7], off offset:160
	s_waitcnt lgkmcnt(3)
	v_add_f32_e32 v6, v64, v32
	v_mul_f32_e32 v9, v8, v6
	v_add_f32_e32 v6, v65, v33
	v_mul_f32_e32 v11, v8, v6
	s_waitcnt lgkmcnt(2)
	v_add_f32_e32 v6, v66, v36
	v_mul_f32_e32 v12, v8, v6
	v_add_f32_e32 v6, v67, v37
	v_mul_f32_e32 v7, v8, v6
	v_cvt_pk_bf16_f32 v6, v9, v11
	v_cvt_pk_bf16_f32 v7, v12, v7
	global_store_dwordx2 v[4:5], v[6:7], off offset:192
	s_waitcnt lgkmcnt(1)
	v_add_f32_e32 v6, v20, v40
	v_mul_f32_e32 v9, v8, v6
	v_add_f32_e32 v6, v21, v41
	v_mul_f32_e32 v11, v8, v6
	s_waitcnt lgkmcnt(0)
	v_add_f32_e32 v6, v22, v44
	v_mul_f32_e32 v10, v8, v6
	v_add_f32_e32 v6, v23, v45
	v_mul_f32_e32 v7, v8, v6
	v_cvt_pk_bf16_f32 v6, v9, v11
	v_cvt_pk_bf16_f32 v7, v10, v7
	global_store_dwordx2 v[4:5], v[6:7], off offset:224
	s_branch .LBB0_44
